# P8 epilogue: conv weights/bias staged to spare LDS by LDS-DMA at tile start (double-buffered), read with ds_read instead of 16 global loads and vmcnt(0) drains
# speedup vs baseline: 1.0187x; 1.0081x over previous
.LBB0_1093:
	s_lshl_b32 s4, s4, 5
	s_and_b32 s10, s4, 0x60
	s_lshl_b32 s6, s55, 13
	s_lshl_b32 s7, s10, 7
	s_add_u32 s22, s18, 0xa5b8000
	s_addc_u32 s23, s19, 0
	s_add_u32 s24, s18, 0x15b38000
	s_addc_u32 s25, s19, 0
	s_add_u32 s26, s18, 0x17138000
	s_addc_u32 s27, s19, 0
	s_add_u32 s28, s18, 0x18738000
	s_addc_u32 s29, s19, 0
	s_ashr_i32 s63, s33, 31
	s_add_u32 s30, s12, 0xb000
	s_addc_u32 s31, s13, 0
	s_add_u32 s34, s12, 0x16000
	s_mov_b64 s[36:37], 0x80
	s_addc_u32 s35, s13, 0
	s_add_i32 m0, s21, 0x18000
	v_lshl_add_u64 v[8:9], v[8:9], 0, s[36:37]
	s_waitcnt vmcnt(4)
	s_barrier
	global_load_lds_dwordx4 v[8:9], off
	v_lshl_add_u64 v[6:7], v[6:7], 0, s[36:37]
	s_add_i32 m0, s21, 0x1a000
	s_add_i32 s64, s21, 0x8000
	s_add_i32 s65, s21, 0xa000
	global_load_lds_dwordx4 v[6:7], off
	v_lshl_add_u64 v[4:5], v[4:5], 0, s[36:37]
	s_mov_b32 m0, s64
	s_add_u32 s4, s50, 0x80080
	global_load_lds_dwordx4 v[4:5], off
	v_lshl_add_u64 v[2:3], v[2:3], 0, s[36:37]
	s_mov_b32 m0, s65
	s_addc_u32 s5, s51, 0
	global_load_lds_dwordx4 v[2:3], off
	s_add_i32 m0, s21, 0x1c000
	v_lshl_add_u64 v[2:3], s[4:5], 0, v[162:163]
	global_load_lds_dwordx4 v[2:3], off
	v_lshl_add_u64 v[2:3], s[4:5], 0, v[164:165]
	s_add_i32 m0, s21, 0x1e000
	v_lshlrev_b32_e32 v4, 6, v10
	global_load_lds_dwordx4 v[2:3], off
	v_bfe_u32 v2, v10, 4, 2
	v_lshlrev_b32_e32 v3, 4, v2
	s_movk_i32 s4, 0x3c0
	v_lshlrev_b32_e32 v5, 2, v10
	v_and_or_b32 v4, v4, s4, v3
	v_and_b32_e32 v5, 32, v5
	v_lshl_or_b32 v239, v2, 2, s10
	v_lshlrev_b32_e32 v2, 9, v10
	v_bitop3_b32 v236, s7, v4, v5 bitop3:0xf6
	v_and_b32_e32 v2, 0x70000, v2
	v_lshlrev_b32_e32 v4, 12, v13
	v_or3_b32 v2, v11, v2, v4
	v_and_b32_e32 v1, 15, v10
	v_add_u32_e32 v166, v2, v12
	v_lshlrev_b32_e32 v2, 5, v14
	v_lshl_or_b32 v3, v1, 6, v3
	s_waitcnt vmcnt(6)
	v_and_b32_e32 v2, 0xf0000, v2
	v_lshl_or_b32 v6, s55, 6, v1
	v_bitop3_b32 v3, v3, s6, v5 bitop3:0xde
	v_or3_b32 v2, v11, v2, v4
	s_add_i32 s68, 0, 0x10000
	s_add_i32 s69, 0, 0x14000
	v_cmp_gt_u32_e64 s[4:5], 2, v1
	v_cmp_lt_u32_e64 s[6:7], 13, v1
	v_add_u32_e32 v237, -14, v1
	v_cmp_lt_u32_e64 s[8:9], 1, v1
	v_add_u32_e32 v238, 0xffffc000, v6
	s_ashr_i32 s66, s3, 31
	v_mov_b32_e32 v167, v163
	v_add_u32_e32 v170, v2, v12
	v_mov_b32_e32 v171, v163
	v_mov_b64_e32 v[172:173], 0xbb0
	v_mov_b64_e32 v[174:175], 0xbaf
	s_movk_i32 s67, 0x16c
	s_mov_b32 s87, 28
	v_and_b32_e32 v245, 31, v0
	v_lshlrev_b32_e32 v245, 4, v245
	v_bfe_u32 v250, v0, 5, 1
	v_mul_u32_u24_e32 v250, 0x5800, v250
	v_add_u32_e32 v245, v245, v250
	v_lshlrev_b32_e32 v250, 2, v239
	s_mov_b32 s86, 0x20000
	v_add_u32_e32 v240, s68, v236
	v_add_u32_e32 v241, 0, v3
	v_add_u32_e32 v242, s69, v236
	s_movk_i32 s70, 0x5000
	s_mov_b32 s71, 0xb000
	s_movk_i32 s72, 0x2c00
	s_barrier
	s_branch .LBB0_1095
.LBB0_1094:
	s_and_b64 vcc, exec, s[10:11]
	s_mov_b32 s46, s38
	s_mov_b32 s20, s40
	s_mov_b64 s[50:51], s[44:45]
	s_mov_b64 s[48:49], s[42:43]
	s_xor_b32 s86, s86, 0x1000
	s_mov_b32 s87, s88
	s_mov_b64 s[90:91], s[92:93]
	s_cbranch_vccnz .LBB0_1143

.LBB0_1097:
	s_ashr_i32 s41, s40, 31
	v_cmp_lt_i64_e32 vcc, s[42:43], v[172:173]
	s_lshl_b64 s[42:43], s[40:41], 20
	s_add_u32 s42, s57, s42
	s_addc_u32 s43, s58, s43
	s_add_u32 s42, s42, s89
	s_addc_u32 s43, s43, 0
	s_and_b64 s[44:45], vcc, exec
	s_cselect_b32 s41, s43, s49
	s_cselect_b32 s47, s42, s48
	s_ashr_i32 s39, s38, 31
	s_lshl_b64 s[44:45], s[38:39], 20
	s_add_u32 s44, s18, s44
	s_addc_u32 s45, s19, s45
	s_add_u32 s44, s44, s89
	s_addc_u32 s45, s45, 0
	s_and_b64 s[52:53], vcc, exec
	s_cselect_b32 s39, s45, s51
	s_cselect_b32 s73, s44, s50
	s_add_u32 s48, s48, 0x80080
	s_addc_u32 s49, s49, 0
	s_add_u32 s74, s50, 0x100
	v_mov_b32_e32 v2, 0
	s_addc_u32 s75, s51, 0
	s_mov_b32 s80, -2
	s_cmpk_gt_u32 s56, 0xfff
	s_cbranch_scc1 .Lp8_nostage
	s_lshr_b32 s84, s56, 10
	s_mul_i32 s85, s84, 0xb000
	s_add_u32 s94, s12, s85
	s_addc_u32 s95, s13, 0
	s_cmp_eq_u32 s84, 3
	s_cselect_b32 s94, s14, s94
	s_cselect_b32 s95, s15, s95
	s_lshl_b32 s85, s46, 9
	s_add_u32 s94, s94, s85
	s_addc_u32 s95, s95, 0
	s_add_i32 m0, s86, s56
	s_nop 0
	global_load_lds_dwordx4 v245, s[94:95]
.Lp8_nostage:
	v_mov_b32_e32 v3, v2
	v_mov_b32_e32 v4, v2
	v_mov_b32_e32 v5, v2
	v_mov_b32_e32 v6, v2
	v_mov_b32_e32 v7, v2
	v_mov_b32_e32 v8, v2
	v_mov_b32_e32 v9, v2
	v_mov_b32_e32 v10, v2
	v_mov_b32_e32 v11, v2
	v_mov_b32_e32 v12, v2
	v_mov_b32_e32 v13, v2
	v_mov_b32_e32 v14, v2
	v_mov_b32_e32 v15, v2
	v_mov_b32_e32 v16, v2
	v_mov_b32_e32 v17, v2
	v_mov_b32_e32 v22, v2
	v_mov_b32_e32 v23, v2
	v_mov_b32_e32 v24, v2
	v_mov_b32_e32 v25, v2
	v_mov_b32_e32 v30, v2
	v_mov_b32_e32 v31, v2
	v_mov_b32_e32 v32, v2
	v_mov_b32_e32 v33, v2
	v_mov_b32_e32 v38, v2
	v_mov_b32_e32 v39, v2
	v_mov_b32_e32 v40, v2
	v_mov_b32_e32 v41, v2
	v_mov_b32_e32 v46, v2
	v_mov_b32_e32 v47, v2
	v_mov_b32_e32 v48, v2
	v_mov_b32_e32 v49, v2
	v_mov_b32_e32 v18, v2
	v_mov_b32_e32 v19, v2
	v_mov_b32_e32 v20, v2
	v_mov_b32_e32 v21, v2
	v_mov_b32_e32 v26, v2
	v_mov_b32_e32 v27, v2
	v_mov_b32_e32 v28, v2
	v_mov_b32_e32 v29, v2
	v_mov_b32_e32 v34, v2
	v_mov_b32_e32 v35, v2
	v_mov_b32_e32 v36, v2
	v_mov_b32_e32 v37, v2
	v_mov_b32_e32 v42, v2
	v_mov_b32_e32 v43, v2
	v_mov_b32_e32 v44, v2
	v_mov_b32_e32 v45, v2
	v_mov_b32_e32 v50, v2
	v_mov_b32_e32 v51, v2
	v_mov_b32_e32 v52, v2
	v_mov_b32_e32 v53, v2
	v_mov_b32_e32 v54, v2
	v_mov_b32_e32 v55, v2
	v_mov_b32_e32 v56, v2
	v_mov_b32_e32 v57, v2
	v_mov_b32_e32 v58, v2
	v_mov_b32_e32 v59, v2
	v_mov_b32_e32 v60, v2
	v_mov_b32_e32 v61, v2
	v_mov_b32_e32 v62, v2
	v_mov_b32_e32 v63, v2
	v_mov_b32_e32 v64, v2
	v_mov_b32_e32 v65, v2
	v_mov_b32_e32 v66, v2
	v_mov_b32_e32 v67, v2
	v_mov_b32_e32 v68, v2
	v_mov_b32_e32 v69, v2
	v_mov_b32_e32 v70, v2
	v_mov_b32_e32 v71, v2
	v_mov_b32_e32 v72, v2
	v_mov_b32_e32 v73, v2
	v_mov_b32_e32 v74, v2
	v_mov_b32_e32 v75, v2
	v_mov_b32_e32 v76, v2
	v_mov_b32_e32 v77, v2
	v_mov_b32_e32 v78, v2
	v_mov_b32_e32 v79, v2
	v_mov_b32_e32 v80, v2
	v_mov_b32_e32 v81, v2
	v_mov_b32_e32 v86, v2
	v_mov_b32_e32 v87, v2
	v_mov_b32_e32 v88, v2
	v_mov_b32_e32 v89, v2
	v_mov_b32_e32 v94, v2
	v_mov_b32_e32 v95, v2
	v_mov_b32_e32 v96, v2
	v_mov_b32_e32 v97, v2
	v_mov_b32_e32 v102, v2
	v_mov_b32_e32 v103, v2
	v_mov_b32_e32 v104, v2
	v_mov_b32_e32 v105, v2
	v_mov_b32_e32 v110, v2
	v_mov_b32_e32 v111, v2
	v_mov_b32_e32 v112, v2
	v_mov_b32_e32 v113, v2
	v_mov_b32_e32 v82, v2
	v_mov_b32_e32 v83, v2
	v_mov_b32_e32 v84, v2
	v_mov_b32_e32 v85, v2
	v_mov_b32_e32 v90, v2
	v_mov_b32_e32 v91, v2
	v_mov_b32_e32 v92, v2
	v_mov_b32_e32 v93, v2
	v_mov_b32_e32 v98, v2
	v_mov_b32_e32 v99, v2
	v_mov_b32_e32 v100, v2
	v_mov_b32_e32 v101, v2
	v_mov_b32_e32 v106, v2
	v_mov_b32_e32 v107, v2
	v_mov_b32_e32 v108, v2
	v_mov_b32_e32 v109, v2
	v_mov_b32_e32 v114, v2
	v_mov_b32_e32 v115, v2
	v_mov_b32_e32 v116, v2
	v_mov_b32_e32 v117, v2
	v_mov_b32_e32 v118, v2
	v_mov_b32_e32 v119, v2
	v_mov_b32_e32 v120, v2
	v_mov_b32_e32 v121, v2
	v_mov_b32_e32 v122, v2
	v_mov_b32_e32 v123, v2
	v_mov_b32_e32 v124, v2
	v_mov_b32_e32 v125, v2
	v_mov_b32_e32 v126, v2
	v_mov_b32_e32 v127, v2
	v_mov_b32_e32 v128, v2
	v_mov_b32_e32 v129, v2
.LBB0_1098:
	ds_read_b128 v[130:133], v240
	ds_read_b128 v[134:137], v240 offset:1024
	ds_read_b128 v[138:141], v240 offset:2048
	ds_read_b128 v[142:145], v240 offset:3072
	s_add_u32 s50, s48, 0xfff80080
	s_addc_u32 s51, s49, -1
	s_cmp_eq_u32 s80, s87
	s_cselect_b32 s53, s41, s51
	s_cselect_b32 s52, s47, s50
	s_cselect_b32 s51, s39, s75
	s_cselect_b32 s50, s73, s74
	v_lshl_add_u64 v[168:169], s[48:49], 0, v[166:167]
	s_add_i32 m0, s21, 0xc000
	ds_read_b128 v[146:149], v241
	ds_read_b128 v[150:153], v241 offset:1024
	ds_read_b128 v[154:157], v241 offset:2048
	ds_read_b128 v[158:161], v241 offset:3072
	ds_read_b128 v[176:179], v241 offset:4096
	ds_read_b128 v[180:183], v241 offset:5120
	ds_read_b128 v[184:187], v241 offset:6144
	ds_read_b128 v[188:191], v241 offset:7168
	global_load_lds_dwordx4 v[168:169], off
	v_lshl_add_u64 v[168:169], s[48:49], 0, v[170:171]
	s_add_i32 m0, s21, 0xe000
	s_nop 0
	global_load_lds_dwordx4 v[168:169], off
	s_waitcnt lgkmcnt(8)
	s_barrier
	s_waitcnt lgkmcnt(0)
	s_setprio 1
	s_waitcnt lgkmcnt(0)
	v_mfma_f32_16x16x32_bf16 v[126:129], v[130:133], v[146:149], v[126:129]
	v_mfma_f32_16x16x32_bf16 v[122:125], v[138:141], v[146:149], v[122:125]
	v_mfma_f32_16x16x32_bf16 v[118:121], v[130:133], v[154:157], v[118:121]
	v_mfma_f32_16x16x32_bf16 v[114:117], v[138:141], v[154:157], v[114:117]
	v_mfma_f32_16x16x32_bf16 v[106:109], v[130:133], v[176:179], v[106:109]
	v_mfma_f32_16x16x32_bf16 v[98:101], v[138:141], v[176:179], v[98:101]
	v_mfma_f32_16x16x32_bf16 v[90:93], v[130:133], v[184:187], v[90:93]
	v_mfma_f32_16x16x32_bf16 v[82:85], v[138:141], v[184:187], v[82:85]
	v_mfma_f32_16x16x32_bf16 v[126:129], v[134:137], v[150:153], v[126:129]
	v_mfma_f32_16x16x32_bf16 v[122:125], v[142:145], v[150:153], v[122:125]
	v_mfma_f32_16x16x32_bf16 v[118:121], v[134:137], v[158:161], v[118:121]
	v_mfma_f32_16x16x32_bf16 v[114:117], v[142:145], v[158:161], v[114:117]
	v_mfma_f32_16x16x32_bf16 v[106:109], v[134:137], v[180:183], v[106:109]
	v_mfma_f32_16x16x32_bf16 v[98:101], v[142:145], v[180:183], v[98:101]
	v_mfma_f32_16x16x32_bf16 v[90:93], v[134:137], v[188:191], v[90:93]
	v_mfma_f32_16x16x32_bf16 v[82:85], v[142:145], v[188:191], v[82:85]
	s_setprio 0
	s_barrier
	s_add_i32 s81, s68, s56
	v_lshl_add_u64 v[168:169], s[50:51], 0, v[162:163]
	s_mov_b32 m0, s81
	ds_read_b128 v[192:195], v242
	ds_read_b128 v[196:199], v242 offset:1024
	ds_read_b128 v[200:203], v242 offset:2048
	ds_read_b128 v[204:207], v242 offset:3072
	global_load_lds_dwordx4 v[168:169], off
	v_lshl_add_u64 v[208:209], s[50:51], 0, v[164:165]
	s_add_i32 m0, s81, 0x2000
	s_nop 0
	global_load_lds_dwordx4 v[208:209], off
	s_barrier
	s_waitcnt lgkmcnt(0)
	s_setprio 1
	s_waitcnt lgkmcnt(0)
	v_mfma_f32_16x16x32_bf16 v[110:113], v[192:195], v[146:149], v[110:113]
	v_mfma_f32_16x16x32_bf16 v[102:105], v[200:203], v[146:149], v[102:105]
	v_mfma_f32_16x16x32_bf16 v[94:97], v[192:195], v[154:157], v[94:97]
	v_mfma_f32_16x16x32_bf16 v[86:89], v[200:203], v[154:157], v[86:89]
	v_mfma_f32_16x16x32_bf16 v[78:81], v[192:195], v[176:179], v[78:81]
	v_mfma_f32_16x16x32_bf16 v[74:77], v[200:203], v[176:179], v[74:77]
	v_mfma_f32_16x16x32_bf16 v[70:73], v[192:195], v[184:187], v[70:73]
	v_mfma_f32_16x16x32_bf16 v[66:69], v[200:203], v[184:187], v[66:69]
	v_mfma_f32_16x16x32_bf16 v[110:113], v[196:199], v[150:153], v[110:113]
	v_mfma_f32_16x16x32_bf16 v[102:105], v[204:207], v[150:153], v[102:105]
	v_mfma_f32_16x16x32_bf16 v[94:97], v[196:199], v[158:161], v[94:97]
	v_mfma_f32_16x16x32_bf16 v[86:89], v[204:207], v[158:161], v[86:89]
	v_mfma_f32_16x16x32_bf16 v[78:81], v[196:199], v[180:183], v[78:81]
	v_mfma_f32_16x16x32_bf16 v[74:77], v[204:207], v[180:183], v[74:77]
	v_mfma_f32_16x16x32_bf16 v[70:73], v[196:199], v[188:191], v[70:73]
	v_mfma_f32_16x16x32_bf16 v[66:69], v[204:207], v[188:191], v[66:69]
	s_setprio 0
	s_mov_b32 m0, s21
	v_lshl_add_u64 v[210:211], s[52:53], 0, v[162:163]
	s_barrier
	ds_read_b128 v[146:149], v241 offset:16384
	ds_read_b128 v[150:153], v241 offset:17408
	ds_read_b128 v[154:157], v241 offset:18432
	ds_read_b128 v[158:161], v241 offset:19456
	ds_read_b128 v[176:179], v241 offset:20480
	ds_read_b128 v[180:183], v241 offset:21504
	ds_read_b128 v[184:187], v241 offset:22528
	ds_read_b128 v[188:191], v241 offset:23552
	global_load_lds_dwordx4 v[210:211], off
	v_lshl_add_u64 v[212:213], s[52:53], 0, v[164:165]
	s_mov_b32 m0, s59
	s_nop 0
	global_load_lds_dwordx4 v[212:213], off
	s_barrier
	s_waitcnt lgkmcnt(0)
	s_setprio 1
	s_waitcnt lgkmcnt(0)
	v_mfma_f32_16x16x32_bf16 v[62:65], v[130:133], v[146:149], v[62:65]
	v_mfma_f32_16x16x32_bf16 v[58:61], v[138:141], v[146:149], v[58:61]
	v_mfma_f32_16x16x32_bf16 v[54:57], v[130:133], v[154:157], v[54:57]
	v_mfma_f32_16x16x32_bf16 v[50:53], v[138:141], v[154:157], v[50:53]
	v_mfma_f32_16x16x32_bf16 v[42:45], v[130:133], v[176:179], v[42:45]
	v_mfma_f32_16x16x32_bf16 v[34:37], v[138:141], v[176:179], v[34:37]
	v_mfma_f32_16x16x32_bf16 v[26:29], v[130:133], v[184:187], v[26:29]
	v_mfma_f32_16x16x32_bf16 v[18:21], v[138:141], v[184:187], v[18:21]
	v_mfma_f32_16x16x32_bf16 v[62:65], v[134:137], v[150:153], v[62:65]
	v_mfma_f32_16x16x32_bf16 v[58:61], v[142:145], v[150:153], v[58:61]
	v_mfma_f32_16x16x32_bf16 v[54:57], v[134:137], v[158:161], v[54:57]
	v_mfma_f32_16x16x32_bf16 v[50:53], v[142:145], v[158:161], v[50:53]
	v_mfma_f32_16x16x32_bf16 v[42:45], v[134:137], v[180:183], v[42:45]
	v_mfma_f32_16x16x32_bf16 v[34:37], v[142:145], v[180:183], v[34:37]
	v_mfma_f32_16x16x32_bf16 v[26:29], v[134:137], v[188:191], v[26:29]
	v_mfma_f32_16x16x32_bf16 v[18:21], v[142:145], v[188:191], v[18:21]
	s_setprio 0
	s_barrier
	s_add_u32 s82, s50, 0x80000
	s_addc_u32 s83, s51, 0
	s_add_i32 s81, s69, s56
	v_lshl_add_u64 v[130:131], s[82:83], 0, v[162:163]
	s_mov_b32 m0, s81
	s_nop 0
	global_load_lds_dwordx4 v[130:131], off
	v_lshl_add_u64 v[130:131], s[82:83], 0, v[164:165]
	s_add_i32 m0, s81, 0x2000
	s_nop 0
	global_load_lds_dwordx4 v[130:131], off
	s_waitcnt vmcnt(6)
	s_barrier
	s_setprio 1
	v_mfma_f32_16x16x32_bf16 v[46:49], v[192:195], v[146:149], v[46:49]
	v_mfma_f32_16x16x32_bf16 v[38:41], v[200:203], v[146:149], v[38:41]
	v_mfma_f32_16x16x32_bf16 v[30:33], v[192:195], v[154:157], v[30:33]
	v_mfma_f32_16x16x32_bf16 v[22:25], v[200:203], v[154:157], v[22:25]
	v_mfma_f32_16x16x32_bf16 v[14:17], v[192:195], v[176:179], v[14:17]
	v_mfma_f32_16x16x32_bf16 v[10:13], v[200:203], v[176:179], v[10:13]
	v_mfma_f32_16x16x32_bf16 v[6:9], v[192:195], v[184:187], v[6:9]
	v_mfma_f32_16x16x32_bf16 v[2:5], v[200:203], v[184:187], v[2:5]
	v_mfma_f32_16x16x32_bf16 v[46:49], v[196:199], v[150:153], v[46:49]
	v_mfma_f32_16x16x32_bf16 v[38:41], v[204:207], v[150:153], v[38:41]
	v_mfma_f32_16x16x32_bf16 v[30:33], v[196:199], v[158:161], v[30:33]
	v_mfma_f32_16x16x32_bf16 v[22:25], v[204:207], v[158:161], v[22:25]
	v_mfma_f32_16x16x32_bf16 v[14:17], v[196:199], v[180:183], v[14:17]
	v_mfma_f32_16x16x32_bf16 v[10:13], v[204:207], v[180:183], v[10:13]
	v_mfma_f32_16x16x32_bf16 v[6:9], v[196:199], v[188:191], v[6:9]
	v_mfma_f32_16x16x32_bf16 v[2:5], v[204:207], v[188:191], v[2:5]
	s_setprio 0
	s_add_i32 s81, 0, 0x18000
	v_add_u32_e32 v142, s81, v236
	s_barrier
	ds_read_b128 v[130:133], v142
	ds_read_b128 v[134:137], v142 offset:1024
	ds_read_b128 v[138:141], v142 offset:2048
	ds_read_b128 v[142:145], v142 offset:3072
	s_add_u32 s52, s52, 0x80000
	s_addc_u32 s53, s53, 0
	s_mov_b32 m0, s60
	v_lshl_add_u64 v[192:193], s[52:53], 0, v[162:163]
	ds_read_b128 v[146:149], v241 offset:32768
	ds_read_b128 v[150:153], v241 offset:33792
	ds_read_b128 v[154:157], v241 offset:34816
	ds_read_b128 v[158:161], v241 offset:35840
	ds_read_b128 v[176:179], v241 offset:36864
	ds_read_b128 v[180:183], v241 offset:37888
	ds_read_b128 v[184:187], v241 offset:38912
	ds_read_b128 v[188:191], v241 offset:39936
	global_load_lds_dwordx4 v[192:193], off
	v_lshl_add_u64 v[192:193], s[52:53], 0, v[164:165]
	s_mov_b32 m0, s61
	s_nop 0
	global_load_lds_dwordx4 v[192:193], off
	s_waitcnt lgkmcnt(8)
	s_barrier
	s_waitcnt lgkmcnt(0)
	s_setprio 1
	s_waitcnt lgkmcnt(0)
	v_mfma_f32_16x16x32_bf16 v[126:129], v[130:133], v[146:149], v[126:129]
	v_mfma_f32_16x16x32_bf16 v[122:125], v[138:141], v[146:149], v[122:125]
	v_mfma_f32_16x16x32_bf16 v[118:121], v[130:133], v[154:157], v[118:121]
	v_mfma_f32_16x16x32_bf16 v[114:117], v[138:141], v[154:157], v[114:117]
	v_mfma_f32_16x16x32_bf16 v[106:109], v[130:133], v[176:179], v[106:109]
	v_mfma_f32_16x16x32_bf16 v[98:101], v[138:141], v[176:179], v[98:101]
	v_mfma_f32_16x16x32_bf16 v[90:93], v[130:133], v[184:187], v[90:93]
	v_mfma_f32_16x16x32_bf16 v[82:85], v[138:141], v[184:187], v[82:85]
	v_mfma_f32_16x16x32_bf16 v[126:129], v[134:137], v[150:153], v[126:129]
	v_mfma_f32_16x16x32_bf16 v[122:125], v[142:145], v[150:153], v[122:125]
	v_mfma_f32_16x16x32_bf16 v[118:121], v[134:137], v[158:161], v[118:121]
	v_mfma_f32_16x16x32_bf16 v[114:117], v[142:145], v[158:161], v[114:117]
	v_mfma_f32_16x16x32_bf16 v[106:109], v[134:137], v[180:183], v[106:109]
	v_mfma_f32_16x16x32_bf16 v[98:101], v[142:145], v[180:183], v[98:101]
	v_mfma_f32_16x16x32_bf16 v[90:93], v[134:137], v[188:191], v[90:93]
	v_mfma_f32_16x16x32_bf16 v[82:85], v[142:145], v[188:191], v[82:85]
	s_setprio 0
	s_barrier
	s_add_i32 s52, 0, 0x1c000
	s_add_i32 s53, s81, s56
	v_add_u32_e32 v204, s52, v236
	v_lshl_add_u64 v[168:169], v[168:169], 0, s[36:37]
	s_mov_b32 m0, s53
	ds_read_b128 v[192:195], v204
	ds_read_b128 v[196:199], v204 offset:1024
	ds_read_b128 v[200:203], v204 offset:2048
	ds_read_b128 v[204:207], v204 offset:3072
	global_load_lds_dwordx4 v[168:169], off
	v_lshl_add_u64 v[168:169], v[208:209], 0, s[36:37]
	s_add_i32 m0, s53, 0x2000
	s_nop 0
	global_load_lds_dwordx4 v[168:169], off
	s_barrier
	s_waitcnt lgkmcnt(0)
	s_setprio 1
	s_waitcnt lgkmcnt(0)
	v_mfma_f32_16x16x32_bf16 v[110:113], v[192:195], v[146:149], v[110:113]
	v_mfma_f32_16x16x32_bf16 v[102:105], v[200:203], v[146:149], v[102:105]
	v_mfma_f32_16x16x32_bf16 v[94:97], v[192:195], v[154:157], v[94:97]
	v_mfma_f32_16x16x32_bf16 v[86:89], v[200:203], v[154:157], v[86:89]
	v_mfma_f32_16x16x32_bf16 v[78:81], v[192:195], v[176:179], v[78:81]
	v_mfma_f32_16x16x32_bf16 v[74:77], v[200:203], v[176:179], v[74:77]
	v_mfma_f32_16x16x32_bf16 v[70:73], v[192:195], v[184:187], v[70:73]
	v_mfma_f32_16x16x32_bf16 v[66:69], v[200:203], v[184:187], v[66:69]
	v_mfma_f32_16x16x32_bf16 v[110:113], v[196:199], v[150:153], v[110:113]
	v_mfma_f32_16x16x32_bf16 v[102:105], v[204:207], v[150:153], v[102:105]
	v_mfma_f32_16x16x32_bf16 v[94:97], v[196:199], v[158:161], v[94:97]
	v_mfma_f32_16x16x32_bf16 v[86:89], v[204:207], v[158:161], v[86:89]
	v_mfma_f32_16x16x32_bf16 v[78:81], v[196:199], v[180:183], v[78:81]
	v_mfma_f32_16x16x32_bf16 v[74:77], v[204:207], v[180:183], v[74:77]
	v_mfma_f32_16x16x32_bf16 v[70:73], v[196:199], v[188:191], v[70:73]
	v_mfma_f32_16x16x32_bf16 v[66:69], v[204:207], v[188:191], v[66:69]
	s_setprio 0
	s_mov_b32 m0, s64
	v_lshl_add_u64 v[168:169], v[210:211], 0, s[36:37]
	s_barrier
	ds_read_b128 v[146:149], v241 offset:49152
	ds_read_b128 v[150:153], v241 offset:50176
	ds_read_b128 v[154:157], v241 offset:51200
	ds_read_b128 v[158:161], v241 offset:52224
	ds_read_b128 v[176:179], v241 offset:53248
	ds_read_b128 v[180:183], v241 offset:54272
	ds_read_b128 v[184:187], v241 offset:55296
	ds_read_b128 v[188:191], v241 offset:56320
	global_load_lds_dwordx4 v[168:169], off
	v_lshl_add_u64 v[168:169], v[212:213], 0, s[36:37]
	s_mov_b32 m0, s65
	s_nop 0
	global_load_lds_dwordx4 v[168:169], off
	s_barrier
	s_waitcnt lgkmcnt(0)
	s_setprio 1
	s_waitcnt lgkmcnt(0)
	v_mfma_f32_16x16x32_bf16 v[62:65], v[130:133], v[146:149], v[62:65]
	v_mfma_f32_16x16x32_bf16 v[58:61], v[138:141], v[146:149], v[58:61]
	v_mfma_f32_16x16x32_bf16 v[54:57], v[130:133], v[154:157], v[54:57]
	v_mfma_f32_16x16x32_bf16 v[50:53], v[138:141], v[154:157], v[50:53]
	v_mfma_f32_16x16x32_bf16 v[42:45], v[130:133], v[176:179], v[42:45]
	v_mfma_f32_16x16x32_bf16 v[34:37], v[138:141], v[176:179], v[34:37]
	v_mfma_f32_16x16x32_bf16 v[26:29], v[130:133], v[184:187], v[26:29]
	v_mfma_f32_16x16x32_bf16 v[18:21], v[138:141], v[184:187], v[18:21]
	v_mfma_f32_16x16x32_bf16 v[62:65], v[134:137], v[150:153], v[62:65]
	v_mfma_f32_16x16x32_bf16 v[58:61], v[142:145], v[150:153], v[58:61]
	v_mfma_f32_16x16x32_bf16 v[54:57], v[134:137], v[158:161], v[54:57]
	v_mfma_f32_16x16x32_bf16 v[50:53], v[142:145], v[158:161], v[50:53]
	v_mfma_f32_16x16x32_bf16 v[42:45], v[134:137], v[180:183], v[42:45]
	v_mfma_f32_16x16x32_bf16 v[34:37], v[142:145], v[180:183], v[34:37]
	v_mfma_f32_16x16x32_bf16 v[26:29], v[134:137], v[188:191], v[26:29]
	v_mfma_f32_16x16x32_bf16 v[18:21], v[142:145], v[188:191], v[18:21]
	s_setprio 0
	s_barrier
	s_add_u32 s50, s50, 0x80080
	s_addc_u32 s51, s51, 0
	s_add_i32 s52, s52, s56
	v_lshl_add_u64 v[130:131], s[50:51], 0, v[162:163]
	s_mov_b32 m0, s52
	s_nop 0
	global_load_lds_dwordx4 v[130:131], off
	v_lshl_add_u64 v[130:131], s[50:51], 0, v[164:165]
	s_add_i32 m0, s52, 0x2000
	s_nop 0
	global_load_lds_dwordx4 v[130:131], off
	s_waitcnt vmcnt(6)
	s_barrier
	s_setprio 1
	v_mfma_f32_16x16x32_bf16 v[46:49], v[192:195], v[146:149], v[46:49]
	v_mfma_f32_16x16x32_bf16 v[38:41], v[200:203], v[146:149], v[38:41]
	v_mfma_f32_16x16x32_bf16 v[30:33], v[192:195], v[154:157], v[30:33]
	v_mfma_f32_16x16x32_bf16 v[22:25], v[200:203], v[154:157], v[22:25]
	v_mfma_f32_16x16x32_bf16 v[14:17], v[192:195], v[176:179], v[14:17]
	v_mfma_f32_16x16x32_bf16 v[10:13], v[200:203], v[176:179], v[10:13]
	v_mfma_f32_16x16x32_bf16 v[6:9], v[192:195], v[184:187], v[6:9]
	v_mfma_f32_16x16x32_bf16 v[2:5], v[200:203], v[184:187], v[2:5]
	v_mfma_f32_16x16x32_bf16 v[46:49], v[196:199], v[150:153], v[46:49]
	v_mfma_f32_16x16x32_bf16 v[38:41], v[204:207], v[150:153], v[38:41]
	v_mfma_f32_16x16x32_bf16 v[30:33], v[196:199], v[158:161], v[30:33]
	v_mfma_f32_16x16x32_bf16 v[22:25], v[204:207], v[158:161], v[22:25]
	v_mfma_f32_16x16x32_bf16 v[14:17], v[196:199], v[180:183], v[14:17]
	v_mfma_f32_16x16x32_bf16 v[10:13], v[204:207], v[180:183], v[10:13]
	v_mfma_f32_16x16x32_bf16 v[6:9], v[196:199], v[188:191], v[6:9]
	v_mfma_f32_16x16x32_bf16 v[2:5], v[204:207], v[188:191], v[2:5]
	s_setprio 0
	s_add_i32 s80, s80, 2
	s_add_u32 s48, s48, 0x100
	s_addc_u32 s49, s49, 0
	s_add_u32 s74, s74, 0x100
	s_addc_u32 s75, s75, 0
	s_cmp_gt_u32 s80, s87
	s_barrier
	s_cbranch_scc0 .LBB0_1098
	v_lshl_or_b32 v176, s46, 7, v239
	s_cmp_gt_i32 s20, 63
	v_ashrrev_i32_e32 v177, 31, v176
	s_mov_b64 s[46:47], -1
	s_cbranch_scc1 .LBB0_1141
	v_add_u32_e32 v251, s86, v250
	v_lshlrev_b64 v[130:131], 2, v[176:177]
	v_lshl_add_u64 v[186:187], s[12:13], 0, v[130:131]
	v_add_co_u32_e32 v146, vcc, 0x5000, v186
	v_lshl_add_u64 v[184:185], s[30:31], 0, v[130:131]
	s_nop 0
	v_addc_co_u32_e32 v147, vcc, 0, v187, vcc
	v_add_co_u32_e32 v150, vcc, 0x5000, v184
	v_lshl_add_u64 v[182:183], s[34:35], 0, v[130:131]
	v_lshl_add_u64 v[180:181], s[14:15], 0, v[130:131]
	v_addc_co_u32_e32 v151, vcc, 0, v185, vcc
	ds_read_b128 v[134:137], v251
	ds_read_b128 v[142:145], v251 offset:1024
	ds_read_b128 v[138:141], v251 offset:2048
	ds_read_b128 v[130:133], v251 offset:3072
	s_nop 0
	ds_read_b128 v[146:149], v251 offset:512
	s_nop 0
	ds_read_b128 v[154:157], v251 offset:1536
	v_add_co_u32_e32 v150, vcc, 0x5000, v182
	s_lshl_b32 s39, s20, 2
	s_nop 0
	v_addc_co_u32_e32 v151, vcc, 0, v183, vcc
	ds_read_b128 v[158:161], v251 offset:2560
	v_add_co_u32_e32 v150, vcc, 0x5000, v180
	s_add_i32 s39, s39, s55
	s_nop 0
	v_addc_co_u32_e32 v151, vcc, 0, v181, vcc
	ds_read_b128 v[150:153], v251 offset:3584
	s_lshl_b32 s41, s39, 1
	v_add_u32_e32 v168, s41, v1
	v_mad_i64_i32 v[168:169], s[46:47], v168, s71, 0
	v_lshl_add_u64 v[168:169], s[24:25], 0, v[168:169]
	v_mov_b32_dpp v206, v126 row_shr:1 row_mask:0xf bank_mask:0xf bound_ctrl:1
	v_mov_b32_dpp v188, v126 row_shr:2 row_mask:0xf bank_mask:0xf bound_ctrl:1
	v_mov_b32_dpp v200, v126 row_shl:15 row_mask:0xf bank_mask:0xf bound_ctrl:1
	v_mov_b32_dpp v198, v126 row_shl:14 row_mask:0xf bank_mask:0xf bound_ctrl:1
	v_mov_b32_dpp v207, v127 row_shr:1 row_mask:0xf bank_mask:0xf bound_ctrl:1
	v_mov_b32_dpp v189, v127 row_shr:2 row_mask:0xf bank_mask:0xf bound_ctrl:1
	v_mov_b32_dpp v201, v127 row_shl:15 row_mask:0xf bank_mask:0xf bound_ctrl:1
	v_mov_b32_dpp v199, v127 row_shl:14 row_mask:0xf bank_mask:0xf bound_ctrl:1
	v_mov_b32_dpp v210, v128 row_shr:1 row_mask:0xf bank_mask:0xf bound_ctrl:1
	v_mov_b32_dpp v208, v128 row_shr:2 row_mask:0xf bank_mask:0xf bound_ctrl:1
	v_mov_b32_dpp v204, v128 row_shl:15 row_mask:0xf bank_mask:0xf bound_ctrl:1
	v_mov_b32_dpp v202, v128 row_shl:14 row_mask:0xf bank_mask:0xf bound_ctrl:1
	v_mov_b32_dpp v211, v129 row_shr:1 row_mask:0xf bank_mask:0xf bound_ctrl:1
	v_mov_b32_dpp v209, v129 row_shr:2 row_mask:0xf bank_mask:0xf bound_ctrl:1
	v_mov_b32_dpp v205, v129 row_shl:15 row_mask:0xf bank_mask:0xf bound_ctrl:1
	v_mov_b32_dpp v203, v129 row_shl:14 row_mask:0xf bank_mask:0xf bound_ctrl:1
	v_lshl_add_u64 v[178:179], v[176:177], 2, v[168:169]
	s_and_saveexec_b64 s[46:47], s[4:5]
	s_cbranch_execz .LBB0_1102
	global_store_dwordx4 v[178:179], v[126:129], off

.LBB0_1104:
	s_or_b64 exec, exec, s[46:47]
	v_lshl_or_b32 v243, s39, 6, v1
	s_and_saveexec_b64 s[46:47], s[8:9]
	s_cbranch_execz .LBB0_1106
	v_pk_add_f32 v[206:207], v[206:207], 0 op_sel_hi:[1,0]
	v_pk_add_f32 v[210:211], v[210:211], 0 op_sel_hi:[1,0]
	s_waitcnt lgkmcnt(0)
	v_pk_mul_f32 v[206:207], v[142:143], v[206:207]
	v_pk_add_f32 v[188:189], v[188:189], 0 op_sel_hi:[1,0]
	v_pk_mul_f32 v[210:211], v[144:145], v[210:211]
	v_pk_fma_f32 v[206:207], v[126:127], v[138:139], v[206:207]
	v_pk_add_f32 v[208:209], v[208:209], 0 op_sel_hi:[1,0]
	v_pk_fma_f32 v[210:211], v[128:129], v[140:141], v[210:211]
	v_pk_fma_f32 v[188:189], v[134:135], v[188:189], v[206:207]
	v_pk_fma_f32 v[206:207], v[136:137], v[208:209], v[210:211]
	v_pk_add_f32 v[188:189], v[130:131], v[188:189]
	v_pk_add_f32 v[206:207], v[132:133], v[206:207]
	v_mul_f32_e32 v208, 0xbfb8aa3b, v188
	v_mul_f32_e32 v209, 0xbfb8aa3b, v189
	v_exp_f32_e32 v208, v208
	v_exp_f32_e32 v209, v209
	v_mul_f32_e32 v210, 0xbfb8aa3b, v206
	v_mul_f32_e32 v211, 0xbfb8aa3b, v207
	v_exp_f32_e32 v210, v210
	v_exp_f32_e32 v211, v211
	v_add_f32_e32 v208, 1.0, v208
	v_add_f32_e32 v209, 1.0, v209
	v_pk_add_f32 v[168:169], v[214:215], 0 op_sel_hi:[1,0]
	v_rcp_f32_e32 v208, v208
	v_rcp_f32_e32 v209, v209
	v_add_f32_e32 v210, 1.0, v210
	v_add_f32_e32 v211, 1.0, v211
	v_pk_add_f32 v[214:215], v[218:219], 0 op_sel_hi:[1,0]
	v_pk_mul_f32 v[168:169], v[154:155], v[168:169]
	v_rcp_f32_e32 v210, v210
	v_rcp_f32_e32 v211, v211
	v_pk_add_f32 v[212:213], v[212:213], 0 op_sel_hi:[1,0]
	v_pk_mul_f32 v[214:215], v[156:157], v[214:215]
	v_pk_fma_f32 v[168:169], v[110:111], v[158:159], v[168:169]
	v_pk_add_f32 v[216:217], v[216:217], 0 op_sel_hi:[1,0]
	v_pk_fma_f32 v[214:215], v[112:113], v[160:161], v[214:215]
	v_pk_fma_f32 v[168:169], v[146:147], v[212:213], v[168:169]
	v_pk_fma_f32 v[212:213], v[148:149], v[216:217], v[214:215]
	v_pk_add_f32 v[168:169], v[150:151], v[168:169]
	v_pk_mul_f32 v[188:189], v[188:189], v[208:209]
	v_pk_add_f32 v[212:213], v[152:153], v[212:213]
	v_pk_mul_f32 v[168:169], v[188:189], v[168:169]
	v_pk_mul_f32 v[188:189], v[206:207], v[210:211]
	v_cvt_pk_bf16_f32 v168, v168, v169
	v_pk_mul_f32 v[188:189], v[188:189], v[212:213]
	s_nop 0
	v_cvt_pk_bf16_f32 v169, v188, v189
	v_mov_b64_e32 v[188:189], s[22:23]
	v_mad_i64_i32 v[188:189], s[48:49], v243, s72, v[188:189]
	v_lshl_add_u64 v[188:189], v[176:177], 1, v[188:189]
	global_store_dwordx2 v[188:189], v[168:169], off
.LBB0_1106:
	s_or_b64 exec, exec, s[46:47]
	v_add_u32_e32 v168, s41, v237
	v_mad_i64_i32 v[188:189], s[46:47], v168, s71, 0
	s_nop 0
	v_mov_b32_dpp v168, v118 row_shr:1 row_mask:0xf bank_mask:0xf bound_ctrl:1
	v_mov_b32_dpp v169, v119 row_shr:1 row_mask:0xf bank_mask:0xf bound_ctrl:1
	v_mov_b32_dpp v212, v120 row_shr:1 row_mask:0xf bank_mask:0xf bound_ctrl:1
	v_mov_b32_dpp v213, v121 row_shr:1 row_mask:0xf bank_mask:0xf bound_ctrl:1
	v_mov_b32_dpp v214, v120 row_shr:2 row_mask:0xf bank_mask:0xf bound_ctrl:1
	v_pk_add_f32 v[204:205], v[204:205], v[212:213]
	v_pk_add_f32 v[168:169], v[200:201], v[168:169]
	v_mov_b32_dpp v215, v121 row_shr:2 row_mask:0xf bank_mask:0xf bound_ctrl:1
	v_mov_b32_dpp v206, v118 row_shr:2 row_mask:0xf bank_mask:0xf bound_ctrl:1
	v_mov_b32_dpp v207, v119 row_shr:2 row_mask:0xf bank_mask:0xf bound_ctrl:1
	v_pk_add_f32 v[200:201], v[202:203], v[214:215]
	s_waitcnt lgkmcnt(0)
	v_pk_mul_f32 v[168:169], v[142:143], v[168:169]
	v_pk_mul_f32 v[202:203], v[144:145], v[204:205]
	v_pk_add_f32 v[198:199], v[198:199], v[206:207]
	v_pk_fma_f32 v[202:203], v[120:121], v[140:141], v[202:203]
	v_pk_fma_f32 v[168:169], v[118:119], v[138:139], v[168:169]
	v_mov_b32_dpp v204, v96 row_shr:1 row_mask:0xf bank_mask:0xf bound_ctrl:1
	v_pk_fma_f32 v[168:169], v[134:135], v[198:199], v[168:169]
	v_pk_fma_f32 v[198:199], v[136:137], v[200:201], v[202:203]
	v_mov_b32_dpp v200, v94 row_shr:1 row_mask:0xf bank_mask:0xf bound_ctrl:1
	v_mov_b32_dpp v201, v95 row_shr:1 row_mask:0xf bank_mask:0xf bound_ctrl:1
	v_mov_b32_dpp v205, v97 row_shr:1 row_mask:0xf bank_mask:0xf bound_ctrl:1
	v_pk_add_f32 v[196:197], v[196:197], v[204:205]
	v_pk_add_f32 v[192:193], v[192:193], v[200:201]
	v_mov_b32_dpp v202, v94 row_shr:2 row_mask:0xf bank_mask:0xf bound_ctrl:1
	v_mov_b32_dpp v203, v95 row_shr:2 row_mask:0xf bank_mask:0xf bound_ctrl:1
	v_mov_b32_dpp v206, v96 row_shr:2 row_mask:0xf bank_mask:0xf bound_ctrl:1
	v_mov_b32_dpp v207, v97 row_shr:2 row_mask:0xf bank_mask:0xf bound_ctrl:1
	v_pk_mul_f32 v[192:193], v[154:155], v[192:193]
	v_pk_mul_f32 v[196:197], v[156:157], v[196:197]
	v_pk_add_f32 v[168:169], v[130:131], v[168:169]
	v_pk_add_f32 v[194:195], v[194:195], v[206:207]
	v_pk_add_f32 v[190:191], v[190:191], v[202:203]
	v_pk_fma_f32 v[196:197], v[96:97], v[160:161], v[196:197]
	v_pk_fma_f32 v[192:193], v[94:95], v[158:159], v[192:193]
	v_pk_add_f32 v[198:199], v[132:133], v[198:199]
	v_pk_fma_f32 v[190:191], v[146:147], v[190:191], v[192:193]
	v_pk_fma_f32 v[192:193], v[148:149], v[194:195], v[196:197]
	v_mul_f32_e32 v194, 0xbfb8aa3b, v168
	v_mul_f32_e32 v195, 0xbfb8aa3b, v169
	v_exp_f32_e32 v194, v194
	v_exp_f32_e32 v195, v195
	v_mul_f32_e32 v196, 0xbfb8aa3b, v198
	v_mul_f32_e32 v197, 0xbfb8aa3b, v199
	v_exp_f32_e32 v196, v196
	v_exp_f32_e32 v197, v197
	v_add_f32_e32 v194, 1.0, v194
	v_add_f32_e32 v195, 1.0, v195
	v_rcp_f32_e32 v194, v194
	v_rcp_f32_e32 v195, v195
	v_add_f32_e32 v196, 1.0, v196
	v_add_f32_e32 v197, 1.0, v197
	v_rcp_f32_e32 v196, v196
	v_rcp_f32_e32 v197, v197
	v_pk_add_f32 v[190:191], v[150:151], v[190:191]
	v_pk_mul_f32 v[168:169], v[168:169], v[194:195]
	v_pk_add_f32 v[192:193], v[152:153], v[192:193]
	v_pk_mul_f32 v[168:169], v[168:169], v[190:191]
	v_pk_mul_f32 v[190:191], v[198:199], v[196:197]
	v_cvt_pk_bf16_f32 v168, v168, v169
	v_pk_mul_f32 v[190:191], v[190:191], v[192:193]
	v_mov_b64_e32 v[194:195], s[22:23]
	v_cvt_pk_bf16_f32 v169, v190, v191
	v_or_b32_e32 v190, 16, v243
	v_mad_i64_i32 v[190:191], s[46:47], v190, s72, v[194:195]
	v_lshlrev_b64 v[196:197], 1, v[176:177]
	v_lshl_add_u64 v[192:193], v[190:191], 0, v[196:197]
	v_mov_b32_dpp v208, v118 row_shl:15 row_mask:0xf bank_mask:0xf bound_ctrl:1
	v_mov_b32_dpp v209, v119 row_shl:15 row_mask:0xf bank_mask:0xf bound_ctrl:1
	global_store_dwordx2 v[192:193], v[168:169], off
	v_mov_b32_dpp v168, v106 row_shr:1 row_mask:0xf bank_mask:0xf bound_ctrl:1
	v_mov_b32_dpp v169, v107 row_shr:1 row_mask:0xf bank_mask:0xf bound_ctrl:1
	v_mov_b32_dpp v216, v120 row_shl:15 row_mask:0xf bank_mask:0xf bound_ctrl:1
	v_mov_b32_dpp v218, v120 row_shl:14 row_mask:0xf bank_mask:0xf bound_ctrl:1
	v_mov_b32_dpp v217, v121 row_shl:15 row_mask:0xf bank_mask:0xf bound_ctrl:1
	v_mov_b32_dpp v219, v121 row_shl:14 row_mask:0xf bank_mask:0xf bound_ctrl:1
	v_mov_b32_dpp v206, v108 row_shr:1 row_mask:0xf bank_mask:0xf bound_ctrl:1
	v_mov_b32_dpp v224, v108 row_shr:2 row_mask:0xf bank_mask:0xf bound_ctrl:1
	v_mov_b32_dpp v207, v109 row_shr:1 row_mask:0xf bank_mask:0xf bound_ctrl:1
	v_pk_add_f32 v[168:169], v[208:209], v[168:169]
	v_mov_b32_dpp v225, v109 row_shr:2 row_mask:0xf bank_mask:0xf bound_ctrl:1
	v_mov_b32_dpp v210, v118 row_shl:14 row_mask:0xf bank_mask:0xf bound_ctrl:1
	v_mov_b32_dpp v211, v119 row_shl:14 row_mask:0xf bank_mask:0xf bound_ctrl:1
	v_mov_b32_dpp v212, v94 row_shl:15 row_mask:0xf bank_mask:0xf bound_ctrl:1
	v_mov_b32_dpp v213, v95 row_shl:15 row_mask:0xf bank_mask:0xf bound_ctrl:1
	v_mov_b32_dpp v220, v96 row_shl:15 row_mask:0xf bank_mask:0xf bound_ctrl:1
	v_mov_b32_dpp v221, v97 row_shl:15 row_mask:0xf bank_mask:0xf bound_ctrl:1
	v_mov_b32_dpp v204, v106 row_shr:2 row_mask:0xf bank_mask:0xf bound_ctrl:1
	v_mov_b32_dpp v205, v107 row_shr:2 row_mask:0xf bank_mask:0xf bound_ctrl:1
	v_pk_add_f32 v[206:207], v[216:217], v[206:207]
	v_pk_add_f32 v[208:209], v[218:219], v[224:225]
	v_pk_mul_f32 v[168:169], v[142:143], v[168:169]
	v_mov_b32_dpp v218, v78 row_shr:1 row_mask:0xf bank_mask:0xf bound_ctrl:1
	v_mov_b32_dpp v219, v79 row_shr:1 row_mask:0xf bank_mask:0xf bound_ctrl:1
	v_mov_b32_dpp v226, v80 row_shr:1 row_mask:0xf bank_mask:0xf bound_ctrl:1
	v_mov_b32_dpp v227, v81 row_shr:1 row_mask:0xf bank_mask:0xf bound_ctrl:1
	v_pk_add_f32 v[204:205], v[210:211], v[204:205]
	v_pk_mul_f32 v[206:207], v[144:145], v[206:207]
	v_pk_fma_f32 v[168:169], v[106:107], v[138:139], v[168:169]
	v_pk_add_f32 v[220:221], v[220:221], v[226:227]
	v_pk_add_f32 v[212:213], v[212:213], v[218:219]
	v_mov_b32_dpp v214, v94 row_shl:14 row_mask:0xf bank_mask:0xf bound_ctrl:1
	v_mov_b32_dpp v215, v95 row_shl:14 row_mask:0xf bank_mask:0xf bound_ctrl:1
	v_mov_b32_dpp v222, v96 row_shl:14 row_mask:0xf bank_mask:0xf bound_ctrl:1
	v_mov_b32_dpp v223, v97 row_shl:14 row_mask:0xf bank_mask:0xf bound_ctrl:1
	v_pk_fma_f32 v[206:207], v[108:109], v[140:141], v[206:207]
	v_pk_fma_f32 v[168:169], v[134:135], v[204:205], v[168:169]
	v_mov_b32_dpp v224, v78 row_shr:2 row_mask:0xf bank_mask:0xf bound_ctrl:1
	v_mov_b32_dpp v225, v79 row_shr:2 row_mask:0xf bank_mask:0xf bound_ctrl:1
	v_mov_b32_dpp v228, v80 row_shr:2 row_mask:0xf bank_mask:0xf bound_ctrl:1
	v_mov_b32_dpp v229, v81 row_shr:2 row_mask:0xf bank_mask:0xf bound_ctrl:1
	v_pk_mul_f32 v[212:213], v[154:155], v[212:213]
	v_pk_mul_f32 v[220:221], v[156:157], v[220:221]
	v_pk_fma_f32 v[204:205], v[136:137], v[208:209], v[206:207]
	v_pk_add_f32 v[168:169], v[130:131], v[168:169]
	v_pk_add_f32 v[218:219], v[222:223], v[228:229]
	v_pk_add_f32 v[214:215], v[214:215], v[224:225]
	v_pk_fma_f32 v[220:221], v[80:81], v[160:161], v[220:221]
	v_pk_fma_f32 v[212:213], v[78:79], v[158:159], v[212:213]
	v_pk_add_f32 v[216:217], v[132:133], v[204:205]
	v_pk_fma_f32 v[212:213], v[146:147], v[214:215], v[212:213]
	v_pk_fma_f32 v[214:215], v[148:149], v[218:219], v[220:221]
	v_mul_f32_e32 v218, 0xbfb8aa3b, v168
	v_mul_f32_e32 v219, 0xbfb8aa3b, v169
	v_exp_f32_e32 v218, v218
	v_exp_f32_e32 v219, v219
	v_mul_f32_e32 v220, 0xbfb8aa3b, v216
	v_mul_f32_e32 v221, 0xbfb8aa3b, v217
	v_exp_f32_e32 v220, v220
	v_exp_f32_e32 v221, v221
	v_add_f32_e32 v218, 1.0, v218
	v_add_f32_e32 v219, 1.0, v219
	v_rcp_f32_e32 v218, v218
	v_rcp_f32_e32 v219, v219
	v_add_f32_e32 v220, 1.0, v220
	v_add_f32_e32 v221, 1.0, v221
	v_rcp_f32_e32 v220, v220
	v_rcp_f32_e32 v221, v221
	v_pk_add_f32 v[212:213], v[150:151], v[212:213]
	v_pk_mul_f32 v[168:169], v[168:169], v[218:219]
	v_pk_add_f32 v[214:215], v[152:153], v[214:215]
	v_pk_mul_f32 v[168:169], v[168:169], v[212:213]
	v_pk_mul_f32 v[212:213], v[216:217], v[220:221]
	v_cvt_pk_bf16_f32 v168, v168, v169
	v_pk_mul_f32 v[212:213], v[212:213], v[214:215]
	v_mov_b32_dpp v198, v106 row_shl:15 row_mask:0xf bank_mask:0xf bound_ctrl:1
	v_cvt_pk_bf16_f32 v169, v212, v213
	v_or_b32_e32 v212, 32, v243
	v_mad_i64_i32 v[194:195], s[46:47], v212, s72, v[194:195]
	v_lshl_add_u64 v[194:195], v[194:195], 0, v[196:197]
	global_store_dwordx2 v[194:195], v[168:169], off
	v_lshl_add_u64 v[168:169], s[26:27], 0, v[188:189]
	v_mov_b32_dpp v190, v106 row_shl:14 row_mask:0xf bank_mask:0xf bound_ctrl:1
	v_mov_b32_dpp v199, v107 row_shl:15 row_mask:0xf bank_mask:0xf bound_ctrl:1
	v_mov_b32_dpp v191, v107 row_shl:14 row_mask:0xf bank_mask:0xf bound_ctrl:1
	v_mov_b32_dpp v202, v108 row_shl:15 row_mask:0xf bank_mask:0xf bound_ctrl:1
	v_mov_b32_dpp v200, v108 row_shl:14 row_mask:0xf bank_mask:0xf bound_ctrl:1
	v_mov_b32_dpp v203, v109 row_shl:15 row_mask:0xf bank_mask:0xf bound_ctrl:1
	v_mov_b32_dpp v201, v109 row_shl:14 row_mask:0xf bank_mask:0xf bound_ctrl:1
	v_mov_b32_dpp v206, v78 row_shl:15 row_mask:0xf bank_mask:0xf bound_ctrl:1
	v_mov_b32_dpp v204, v78 row_shl:14 row_mask:0xf bank_mask:0xf bound_ctrl:1
	v_mov_b32_dpp v207, v79 row_shl:15 row_mask:0xf bank_mask:0xf bound_ctrl:1
	v_mov_b32_dpp v205, v79 row_shl:14 row_mask:0xf bank_mask:0xf bound_ctrl:1
	v_mov_b32_dpp v210, v80 row_shl:15 row_mask:0xf bank_mask:0xf bound_ctrl:1
	v_mov_b32_dpp v208, v80 row_shl:14 row_mask:0xf bank_mask:0xf bound_ctrl:1
	v_mov_b32_dpp v211, v81 row_shl:15 row_mask:0xf bank_mask:0xf bound_ctrl:1
	v_mov_b32_dpp v209, v81 row_shl:14 row_mask:0xf bank_mask:0xf bound_ctrl:1
	v_mov_b32_dpp v216, v90 row_shr:1 row_mask:0xf bank_mask:0xf bound_ctrl:1
	v_mov_b32_dpp v212, v90 row_shr:2 row_mask:0xf bank_mask:0xf bound_ctrl:1
	v_mov_b32_dpp v217, v91 row_shr:1 row_mask:0xf bank_mask:0xf bound_ctrl:1
	v_mov_b32_dpp v213, v91 row_shr:2 row_mask:0xf bank_mask:0xf bound_ctrl:1
	v_mov_b32_dpp v218, v92 row_shr:1 row_mask:0xf bank_mask:0xf bound_ctrl:1
	v_mov_b32_dpp v214, v92 row_shr:2 row_mask:0xf bank_mask:0xf bound_ctrl:1
	v_mov_b32_dpp v219, v93 row_shr:1 row_mask:0xf bank_mask:0xf bound_ctrl:1
	v_mov_b32_dpp v215, v93 row_shr:2 row_mask:0xf bank_mask:0xf bound_ctrl:1
	v_lshl_add_u64 v[188:189], v[176:177], 2, v[168:169]
	s_and_saveexec_b64 s[46:47], s[6:7]
	s_cbranch_execz .LBB0_1108
	global_store_dwordx4 v[188:189], v[90:93], off

.LBB0_1120:
	s_or_b64 exec, exec, s[46:47]
	v_pk_add_f32 v[168:169], v[220:221], v[234:235]
	v_pk_add_f32 v[216:217], v[216:217], v[232:233]
	v_pk_mul_f32 v[156:157], v[156:157], v[168:169]
	v_pk_mul_f32 v[154:155], v[154:155], v[216:217]
	v_pk_add_f32 v[218:219], v[218:219], v[230:231]
	v_pk_add_f32 v[204:205], v[214:215], v[204:205]
	v_pk_fma_f32 v[156:157], v[8:9], v[160:161], v[156:157]
	v_pk_fma_f32 v[154:155], v[6:7], v[158:159], v[154:155]
	v_pk_fma_f32 v[148:149], v[148:149], v[218:219], v[156:157]
	v_pk_fma_f32 v[146:147], v[146:147], v[204:205], v[154:155]
	v_pk_add_f32 v[148:149], v[152:153], v[148:149]
	v_pk_add_f32 v[146:147], v[150:151], v[146:147]
	v_pk_add_f32 v[150:151], v[212:213], v[228:229]
	v_pk_add_f32 v[152:153], v[208:209], v[226:227]
	v_pk_mul_f32 v[144:145], v[144:145], v[150:151]
	v_pk_mul_f32 v[142:143], v[142:143], v[152:153]
	v_pk_add_f32 v[154:155], v[210:211], v[224:225]
	v_pk_add_f32 v[156:157], v[206:207], v[222:223]
	v_pk_fma_f32 v[140:141], v[28:29], v[140:141], v[144:145]
	v_pk_fma_f32 v[138:139], v[26:27], v[138:139], v[142:143]
	v_pk_fma_f32 v[136:137], v[136:137], v[154:155], v[140:141]
	v_pk_fma_f32 v[134:135], v[134:135], v[156:157], v[138:139]
	v_pk_add_f32 v[132:133], v[132:133], v[136:137]
	v_pk_add_f32 v[130:131], v[130:131], v[134:135]
	v_mul_f32_e32 v136, 0xbfb8aa3b, v132
	v_mul_f32_e32 v134, 0xbfb8aa3b, v130
	v_mul_f32_e32 v135, 0xbfb8aa3b, v131
	v_mul_f32_e32 v137, 0xbfb8aa3b, v133
	v_exp_f32_e32 v134, v134
	v_exp_f32_e32 v135, v135
	v_exp_f32_e32 v136, v136
	v_exp_f32_e32 v137, v137
	v_add_f32_e32 v134, 1.0, v134
	v_add_f32_e32 v135, 1.0, v135
	v_add_f32_e32 v136, 1.0, v136
	v_add_f32_e32 v137, 1.0, v137
	v_rcp_f32_e32 v134, v134
	v_rcp_f32_e32 v135, v135
	v_rcp_f32_e32 v136, v136
	v_rcp_f32_e32 v137, v137
	v_mov_b32_dpp v216, v122 row_shr:1 row_mask:0xf bank_mask:0xf bound_ctrl:1
	v_pk_mul_f32 v[130:131], v[130:131], v[134:135]
	v_or_b32_e32 v134, 48, v244
	v_pk_mul_f32 v[132:133], v[132:133], v[136:137]
	v_pk_mul_f32 v[130:131], v[130:131], v[146:147]
	v_pk_mul_f32 v[132:133], v[132:133], v[148:149]
	v_cvt_pk_bf16_f32 v130, v130, v131
	v_cvt_pk_bf16_f32 v131, v132, v133
	v_mov_b64_e32 v[132:133], s[22:23]
	v_mad_i64_i32 v[132:133], s[46:47], v134, s72, v[132:133]
	v_lshl_add_u64 v[204:205], v[176:177], 1, v[132:133]
	global_store_dwordx2 v[204:205], v[130:131], off
	v_or_b32_e32 v130, 16, v176
	v_add_co_u32_e32 v146, vcc, s70, v186
	v_ashrrev_i32_e32 v131, 31, v130
	s_nop 0
	v_addc_co_u32_e32 v147, vcc, 0, v187, vcc
	v_lshlrev_b64 v[130:131], 2, v[130:131]
	v_add_co_u32_e32 v150, vcc, s70, v184
	v_lshl_add_u64 v[132:133], s[30:31], 0, v[130:131]
	v_lshl_add_u64 v[130:131], s[34:35], 0, v[130:131]
	v_addc_co_u32_e32 v151, vcc, 0, v185, vcc
	ds_read_b128 v[134:137], v251 offset:64
	ds_read_b128 v[142:145], v251 offset:1088
	ds_read_b128 v[138:141], v251 offset:2112
	s_nop 0
	ds_read_b128 v[130:133], v251 offset:3136
	s_nop 0
	ds_read_b128 v[146:149], v251 offset:576
	s_nop 0
	ds_read_b128 v[158:161], v251 offset:1600
	v_add_co_u32_e32 v150, vcc, s70, v182
	v_mov_b32_dpp v214, v122 row_shr:2 row_mask:0xf bank_mask:0xf bound_ctrl:1
	s_nop 0
	v_addc_co_u32_e32 v151, vcc, 0, v183, vcc
	ds_read_b128 v[154:157], v251 offset:2624
	v_add_co_u32_e32 v150, vcc, s70, v180
	v_mov_b32_dpp v208, v122 row_shl:15 row_mask:0xf bank_mask:0xf bound_ctrl:1
	s_nop 0
	v_addc_co_u32_e32 v151, vcc, 0, v181, vcc
	ds_read_b128 v[150:153], v251 offset:3648
	v_mov_b32_dpp v206, v122 row_shl:14 row_mask:0xf bank_mask:0xf bound_ctrl:1
	v_mov_b32_dpp v217, v123 row_shr:1 row_mask:0xf bank_mask:0xf bound_ctrl:1
	v_mov_b32_dpp v215, v123 row_shr:2 row_mask:0xf bank_mask:0xf bound_ctrl:1
	v_mov_b32_dpp v209, v123 row_shl:15 row_mask:0xf bank_mask:0xf bound_ctrl:1
	v_mov_b32_dpp v207, v123 row_shl:14 row_mask:0xf bank_mask:0xf bound_ctrl:1
	v_mov_b32_dpp v220, v124 row_shr:1 row_mask:0xf bank_mask:0xf bound_ctrl:1
	v_mov_b32_dpp v218, v124 row_shr:2 row_mask:0xf bank_mask:0xf bound_ctrl:1
	v_mov_b32_dpp v212, v124 row_shl:15 row_mask:0xf bank_mask:0xf bound_ctrl:1
	v_mov_b32_dpp v210, v124 row_shl:14 row_mask:0xf bank_mask:0xf bound_ctrl:1
	v_mov_b32_dpp v221, v125 row_shr:1 row_mask:0xf bank_mask:0xf bound_ctrl:1
	v_mov_b32_dpp v219, v125 row_shr:2 row_mask:0xf bank_mask:0xf bound_ctrl:1
	v_mov_b32_dpp v213, v125 row_shl:15 row_mask:0xf bank_mask:0xf bound_ctrl:1
	v_mov_b32_dpp v211, v125 row_shl:14 row_mask:0xf bank_mask:0xf bound_ctrl:1
	s_and_saveexec_b64 s[46:47], s[4:5]
	s_cbranch_execz .LBB0_1122
	global_store_dwordx4 v[178:179], v[122:125], off offset:64

.LBB0_1124:
	s_or_b64 exec, exec, s[46:47]
	s_and_saveexec_b64 s[46:47], s[8:9]
	s_cbranch_execz .LBB0_1126
	v_pk_add_f32 v[216:217], v[216:217], 0 op_sel_hi:[1,0]
	v_pk_add_f32 v[220:221], v[220:221], 0 op_sel_hi:[1,0]
	s_waitcnt lgkmcnt(0)
	v_pk_mul_f32 v[216:217], v[142:143], v[216:217]
	v_pk_add_f32 v[214:215], v[214:215], 0 op_sel_hi:[1,0]
	v_pk_mul_f32 v[220:221], v[144:145], v[220:221]
	v_pk_fma_f32 v[216:217], v[122:123], v[138:139], v[216:217]
	v_pk_add_f32 v[218:219], v[218:219], 0 op_sel_hi:[1,0]
	v_pk_fma_f32 v[220:221], v[124:125], v[140:141], v[220:221]
	v_pk_fma_f32 v[214:215], v[134:135], v[214:215], v[216:217]
	v_pk_fma_f32 v[216:217], v[136:137], v[218:219], v[220:221]
	v_pk_add_f32 v[214:215], v[130:131], v[214:215]
	v_pk_add_f32 v[216:217], v[132:133], v[216:217]
	v_mul_f32_e32 v218, 0xbfb8aa3b, v214
	v_mul_f32_e32 v219, 0xbfb8aa3b, v215
	v_exp_f32_e32 v218, v218
	v_exp_f32_e32 v219, v219
	v_mul_f32_e32 v220, 0xbfb8aa3b, v216
	v_mul_f32_e32 v221, 0xbfb8aa3b, v217
	v_exp_f32_e32 v220, v220
	v_exp_f32_e32 v221, v221
	v_add_f32_e32 v218, 1.0, v218
	v_add_f32_e32 v219, 1.0, v219
	v_pk_add_f32 v[168:169], v[224:225], 0 op_sel_hi:[1,0]
	v_rcp_f32_e32 v218, v218
	v_rcp_f32_e32 v219, v219
	v_add_f32_e32 v220, 1.0, v220
	v_add_f32_e32 v221, 1.0, v221
	v_pk_add_f32 v[178:179], v[228:229], 0 op_sel_hi:[1,0]
	v_pk_mul_f32 v[168:169], v[158:159], v[168:169]
	v_rcp_f32_e32 v220, v220
	v_rcp_f32_e32 v221, v221
	v_pk_add_f32 v[222:223], v[222:223], 0 op_sel_hi:[1,0]
	v_pk_mul_f32 v[178:179], v[160:161], v[178:179]
	v_pk_fma_f32 v[168:169], v[102:103], v[154:155], v[168:169]
	v_pk_add_f32 v[224:225], v[226:227], 0 op_sel_hi:[1,0]
	v_pk_fma_f32 v[178:179], v[104:105], v[156:157], v[178:179]
	v_pk_fma_f32 v[168:169], v[146:147], v[222:223], v[168:169]
	v_pk_fma_f32 v[178:179], v[148:149], v[224:225], v[178:179]
	v_pk_add_f32 v[168:169], v[150:151], v[168:169]
	v_pk_mul_f32 v[214:215], v[214:215], v[218:219]
	v_pk_add_f32 v[178:179], v[152:153], v[178:179]
	v_pk_mul_f32 v[168:169], v[214:215], v[168:169]
	v_pk_mul_f32 v[214:215], v[216:217], v[220:221]
	v_cvt_pk_bf16_f32 v168, v168, v169
	v_pk_mul_f32 v[178:179], v[214:215], v[178:179]
	s_nop 0
	v_cvt_pk_bf16_f32 v169, v178, v179
	v_mov_b64_e32 v[178:179], s[22:23]
	v_mad_i64_i32 v[178:179], s[48:49], v243, s72, v[178:179]
	v_lshl_add_u64 v[178:179], v[176:177], 1, v[178:179]
	global_store_dwordx2 v[178:179], v[168:169], off offset:32
.LBB0_1126:
	s_or_b64 exec, exec, s[46:47]
	v_mov_b32_dpp v168, v114 row_shr:1 row_mask:0xf bank_mask:0xf bound_ctrl:1
	v_mov_b32_dpp v169, v115 row_shr:1 row_mask:0xf bank_mask:0xf bound_ctrl:1
	v_mov_b32_dpp v218, v116 row_shr:1 row_mask:0xf bank_mask:0xf bound_ctrl:1
	v_mov_b32_dpp v219, v117 row_shr:1 row_mask:0xf bank_mask:0xf bound_ctrl:1
	v_mov_b32_dpp v178, v114 row_shr:2 row_mask:0xf bank_mask:0xf bound_ctrl:1
	v_mov_b32_dpp v179, v115 row_shr:2 row_mask:0xf bank_mask:0xf bound_ctrl:1
	v_pk_add_f32 v[212:213], v[212:213], v[218:219]
	v_pk_add_f32 v[168:169], v[208:209], v[168:169]
	v_mov_b32_dpp v220, v116 row_shr:2 row_mask:0xf bank_mask:0xf bound_ctrl:1
	v_mov_b32_dpp v221, v117 row_shr:2 row_mask:0xf bank_mask:0xf bound_ctrl:1
	v_pk_add_f32 v[178:179], v[206:207], v[178:179]
	s_waitcnt lgkmcnt(0)
	v_pk_mul_f32 v[168:169], v[142:143], v[168:169]
	v_pk_mul_f32 v[206:207], v[144:145], v[212:213]
	v_pk_add_f32 v[208:209], v[210:211], v[220:221]
	v_pk_fma_f32 v[206:207], v[116:117], v[140:141], v[206:207]
	v_pk_fma_f32 v[168:169], v[114:115], v[138:139], v[168:169]
	v_mov_b32_dpp v218, v88 row_shr:1 row_mask:0xf bank_mask:0xf bound_ctrl:1
	v_pk_fma_f32 v[168:169], v[134:135], v[178:179], v[168:169]
	v_pk_fma_f32 v[178:179], v[136:137], v[208:209], v[206:207]
	v_mov_b32_dpp v206, v86 row_shr:1 row_mask:0xf bank_mask:0xf bound_ctrl:1
	v_mov_b32_dpp v207, v87 row_shr:1 row_mask:0xf bank_mask:0xf bound_ctrl:1
	v_mov_b32_dpp v219, v89 row_shr:1 row_mask:0xf bank_mask:0xf bound_ctrl:1
	v_pk_add_f32 v[186:187], v[186:187], v[218:219]
	v_pk_add_f32 v[182:183], v[182:183], v[206:207]
	v_mov_b32_dpp v208, v86 row_shr:2 row_mask:0xf bank_mask:0xf bound_ctrl:1
	v_mov_b32_dpp v209, v87 row_shr:2 row_mask:0xf bank_mask:0xf bound_ctrl:1
	v_mov_b32_dpp v220, v88 row_shr:2 row_mask:0xf bank_mask:0xf bound_ctrl:1
	v_mov_b32_dpp v221, v89 row_shr:2 row_mask:0xf bank_mask:0xf bound_ctrl:1
	v_pk_mul_f32 v[182:183], v[158:159], v[182:183]
	v_pk_mul_f32 v[186:187], v[160:161], v[186:187]
	v_pk_add_f32 v[178:179], v[132:133], v[178:179]
	v_pk_add_f32 v[168:169], v[130:131], v[168:169]
	v_pk_add_f32 v[184:185], v[184:185], v[220:221]
	v_pk_add_f32 v[180:181], v[180:181], v[208:209]
	v_pk_fma_f32 v[186:187], v[88:89], v[156:157], v[186:187]
	v_pk_fma_f32 v[182:183], v[86:87], v[154:155], v[182:183]
	v_mov_b32_dpp v214, v114 row_shl:15 row_mask:0xf bank_mask:0xf bound_ctrl:1
	v_pk_fma_f32 v[180:181], v[146:147], v[180:181], v[182:183]
	v_pk_fma_f32 v[182:183], v[148:149], v[184:185], v[186:187]
	v_mul_f32_e32 v184, 0xbfb8aa3b, v168
	v_mul_f32_e32 v185, 0xbfb8aa3b, v169
	v_mul_f32_e32 v186, 0xbfb8aa3b, v178
	v_mul_f32_e32 v187, 0xbfb8aa3b, v179
	v_exp_f32_e32 v184, v184
	v_exp_f32_e32 v185, v185
	v_exp_f32_e32 v186, v186
	v_exp_f32_e32 v187, v187
	v_add_f32_e32 v184, 1.0, v184
	v_add_f32_e32 v185, 1.0, v185
	v_add_f32_e32 v186, 1.0, v186
	v_add_f32_e32 v187, 1.0, v187
	v_rcp_f32_e32 v184, v184
	v_rcp_f32_e32 v185, v185
	v_rcp_f32_e32 v186, v186
	v_rcp_f32_e32 v187, v187
	v_pk_add_f32 v[182:183], v[152:153], v[182:183]
	v_pk_add_f32 v[180:181], v[150:151], v[180:181]
	v_pk_mul_f32 v[168:169], v[168:169], v[184:185]
	v_pk_mul_f32 v[178:179], v[178:179], v[186:187]
	v_pk_mul_f32 v[168:169], v[168:169], v[180:181]
	v_pk_mul_f32 v[178:179], v[178:179], v[182:183]
	v_cvt_pk_bf16_f32 v168, v168, v169
	v_cvt_pk_bf16_f32 v169, v178, v179
	v_mov_b32_dpp v215, v115 row_shl:15 row_mask:0xf bank_mask:0xf bound_ctrl:1
	global_store_dwordx2 v[192:193], v[168:169], off offset:32
	v_mov_b32_dpp v168, v98 row_shr:1 row_mask:0xf bank_mask:0xf bound_ctrl:1
	v_mov_b32_dpp v169, v99 row_shr:1 row_mask:0xf bank_mask:0xf bound_ctrl:1
	v_mov_b32_dpp v216, v114 row_shl:14 row_mask:0xf bank_mask:0xf bound_ctrl:1
	v_mov_b32_dpp v217, v115 row_shl:14 row_mask:0xf bank_mask:0xf bound_ctrl:1
	v_mov_b32_dpp v222, v116 row_shl:15 row_mask:0xf bank_mask:0xf bound_ctrl:1
	v_mov_b32_dpp v223, v117 row_shl:15 row_mask:0xf bank_mask:0xf bound_ctrl:1
	v_mov_b32_dpp v186, v98 row_shr:2 row_mask:0xf bank_mask:0xf bound_ctrl:1
	v_mov_b32_dpp v187, v99 row_shr:2 row_mask:0xf bank_mask:0xf bound_ctrl:1
	v_mov_b32_dpp v192, v100 row_shr:1 row_mask:0xf bank_mask:0xf bound_ctrl:1
	v_mov_b32_dpp v193, v101 row_shr:1 row_mask:0xf bank_mask:0xf bound_ctrl:1
	v_pk_add_f32 v[168:169], v[214:215], v[168:169]
	v_mov_b32_dpp v210, v86 row_shl:15 row_mask:0xf bank_mask:0xf bound_ctrl:1
	v_mov_b32_dpp v211, v87 row_shl:15 row_mask:0xf bank_mask:0xf bound_ctrl:1
	v_mov_b32_dpp v226, v88 row_shl:15 row_mask:0xf bank_mask:0xf bound_ctrl:1
	v_mov_b32_dpp v227, v89 row_shl:15 row_mask:0xf bank_mask:0xf bound_ctrl:1
	v_pk_add_f32 v[192:193], v[222:223], v[192:193]
	v_pk_add_f32 v[186:187], v[216:217], v[186:187]
	v_pk_mul_f32 v[168:169], v[142:143], v[168:169]
	v_mov_b32_dpp v216, v74 row_shr:1 row_mask:0xf bank_mask:0xf bound_ctrl:1
	v_mov_b32_dpp v217, v75 row_shr:1 row_mask:0xf bank_mask:0xf bound_ctrl:1
	v_mov_b32_dpp v220, v76 row_shr:1 row_mask:0xf bank_mask:0xf bound_ctrl:1
	v_mov_b32_dpp v221, v77 row_shr:1 row_mask:0xf bank_mask:0xf bound_ctrl:1
	v_mov_b32_dpp v224, v116 row_shl:14 row_mask:0xf bank_mask:0xf bound_ctrl:1
	v_mov_b32_dpp v225, v117 row_shl:14 row_mask:0xf bank_mask:0xf bound_ctrl:1
	v_mov_b32_dpp v212, v86 row_shl:14 row_mask:0xf bank_mask:0xf bound_ctrl:1
	v_mov_b32_dpp v213, v87 row_shl:14 row_mask:0xf bank_mask:0xf bound_ctrl:1
	v_mov_b32_dpp v206, v100 row_shr:2 row_mask:0xf bank_mask:0xf bound_ctrl:1
	v_mov_b32_dpp v207, v101 row_shr:2 row_mask:0xf bank_mask:0xf bound_ctrl:1
	v_pk_mul_f32 v[192:193], v[144:145], v[192:193]
	v_pk_fma_f32 v[168:169], v[98:99], v[138:139], v[168:169]
	v_mov_b32_dpp v218, v74 row_shr:2 row_mask:0xf bank_mask:0xf bound_ctrl:1
	v_mov_b32_dpp v219, v75 row_shr:2 row_mask:0xf bank_mask:0xf bound_ctrl:1
	v_pk_add_f32 v[220:221], v[226:227], v[220:221]
	v_pk_add_f32 v[210:211], v[210:211], v[216:217]
	v_mov_b32_dpp v228, v88 row_shl:14 row_mask:0xf bank_mask:0xf bound_ctrl:1
	v_mov_b32_dpp v229, v89 row_shl:14 row_mask:0xf bank_mask:0xf bound_ctrl:1
	v_pk_add_f32 v[206:207], v[224:225], v[206:207]
	v_pk_fma_f32 v[192:193], v[100:101], v[140:141], v[192:193]
	v_pk_fma_f32 v[168:169], v[134:135], v[186:187], v[168:169]
	v_mov_b32_dpp v222, v76 row_shr:2 row_mask:0xf bank_mask:0xf bound_ctrl:1
	v_mov_b32_dpp v223, v77 row_shr:2 row_mask:0xf bank_mask:0xf bound_ctrl:1
	v_pk_add_f32 v[212:213], v[212:213], v[218:219]
	v_pk_mul_f32 v[210:211], v[158:159], v[210:211]
	v_pk_mul_f32 v[218:219], v[160:161], v[220:221]
	v_pk_fma_f32 v[186:187], v[136:137], v[206:207], v[192:193]
	v_pk_add_f32 v[168:169], v[130:131], v[168:169]
	v_pk_add_f32 v[216:217], v[228:229], v[222:223]
	v_pk_fma_f32 v[218:219], v[76:77], v[156:157], v[218:219]
	v_pk_fma_f32 v[210:211], v[74:75], v[154:155], v[210:211]
	v_pk_add_f32 v[214:215], v[132:133], v[186:187]
	v_pk_fma_f32 v[210:211], v[146:147], v[212:213], v[210:211]
	v_pk_fma_f32 v[212:213], v[148:149], v[216:217], v[218:219]
	v_mul_f32_e32 v216, 0xbfb8aa3b, v168
	v_mul_f32_e32 v217, 0xbfb8aa3b, v169
	v_exp_f32_e32 v216, v216
	v_exp_f32_e32 v217, v217
	v_mul_f32_e32 v218, 0xbfb8aa3b, v214
	v_mul_f32_e32 v219, 0xbfb8aa3b, v215
	v_exp_f32_e32 v218, v218
	v_exp_f32_e32 v219, v219
	v_add_f32_e32 v216, 1.0, v216
	v_add_f32_e32 v217, 1.0, v217
	v_rcp_f32_e32 v216, v216
	v_rcp_f32_e32 v217, v217
	v_add_f32_e32 v218, 1.0, v218
	v_add_f32_e32 v219, 1.0, v219
	v_rcp_f32_e32 v218, v218
	v_rcp_f32_e32 v219, v219
	v_pk_add_f32 v[210:211], v[150:151], v[210:211]
	v_pk_mul_f32 v[168:169], v[168:169], v[216:217]
	v_pk_add_f32 v[212:213], v[152:153], v[212:213]
	v_pk_mul_f32 v[168:169], v[168:169], v[210:211]
	v_pk_mul_f32 v[210:211], v[214:215], v[218:219]
	v_cvt_pk_bf16_f32 v168, v168, v169
	v_pk_mul_f32 v[210:211], v[210:211], v[212:213]
	v_mov_b32_dpp v180, v98 row_shl:15 row_mask:0xf bank_mask:0xf bound_ctrl:1
	v_cvt_pk_bf16_f32 v169, v210, v211
	v_mov_b32_dpp v178, v98 row_shl:14 row_mask:0xf bank_mask:0xf bound_ctrl:1
	v_mov_b32_dpp v181, v99 row_shl:15 row_mask:0xf bank_mask:0xf bound_ctrl:1
	v_mov_b32_dpp v179, v99 row_shl:14 row_mask:0xf bank_mask:0xf bound_ctrl:1
	v_mov_b32_dpp v184, v100 row_shl:15 row_mask:0xf bank_mask:0xf bound_ctrl:1
	v_mov_b32_dpp v182, v100 row_shl:14 row_mask:0xf bank_mask:0xf bound_ctrl:1
	v_mov_b32_dpp v185, v101 row_shl:15 row_mask:0xf bank_mask:0xf bound_ctrl:1
	v_mov_b32_dpp v183, v101 row_shl:14 row_mask:0xf bank_mask:0xf bound_ctrl:1
	v_mov_b32_dpp v192, v74 row_shl:15 row_mask:0xf bank_mask:0xf bound_ctrl:1
	v_mov_b32_dpp v186, v74 row_shl:14 row_mask:0xf bank_mask:0xf bound_ctrl:1
	v_mov_b32_dpp v193, v75 row_shl:15 row_mask:0xf bank_mask:0xf bound_ctrl:1
	v_mov_b32_dpp v187, v75 row_shl:14 row_mask:0xf bank_mask:0xf bound_ctrl:1
	v_mov_b32_dpp v208, v76 row_shl:15 row_mask:0xf bank_mask:0xf bound_ctrl:1
	v_mov_b32_dpp v206, v76 row_shl:14 row_mask:0xf bank_mask:0xf bound_ctrl:1
	v_mov_b32_dpp v209, v77 row_shl:15 row_mask:0xf bank_mask:0xf bound_ctrl:1
	v_mov_b32_dpp v207, v77 row_shl:14 row_mask:0xf bank_mask:0xf bound_ctrl:1
	global_store_dwordx2 v[194:195], v[168:169], off offset:32
	v_mov_b32_dpp v212, v82 row_shr:1 row_mask:0xf bank_mask:0xf bound_ctrl:1
	v_mov_b32_dpp v194, v82 row_shr:2 row_mask:0xf bank_mask:0xf bound_ctrl:1
	v_mov_b32_dpp v213, v83 row_shr:1 row_mask:0xf bank_mask:0xf bound_ctrl:1
	v_mov_b32_dpp v195, v83 row_shr:2 row_mask:0xf bank_mask:0xf bound_ctrl:1
	v_mov_b32_dpp v214, v84 row_shr:1 row_mask:0xf bank_mask:0xf bound_ctrl:1
	v_mov_b32_dpp v210, v84 row_shr:2 row_mask:0xf bank_mask:0xf bound_ctrl:1
	v_mov_b32_dpp v215, v85 row_shr:1 row_mask:0xf bank_mask:0xf bound_ctrl:1
	v_mov_b32_dpp v211, v85 row_shr:2 row_mask:0xf bank_mask:0xf bound_ctrl:1
	s_and_saveexec_b64 s[46:47], s[6:7]
	s_cbranch_execz .LBB0_1128
	global_store_dwordx4 v[188:189], v[82:85], off offset:64
